# memory phases of the two-phase loops retire their own ds_reads (lgkmcnt(0)) before the phase barrier, so the other group's slot refills can never overtake them
# speedup vs baseline: 1.0042x; 1.0026x over previous
.LBB0_103:
	s_ashr_i32 s23, s22, 31
	s_lshl_b64 s[2:3], s[22:23], 19
	s_add_u32 s58, s90, s2
	s_addc_u32 s59, s77, s3
	s_and_b64 s[2:3], s[46:47], exec
	s_cselect_b32 s1, s59, s49
	s_cselect_b32 s23, s58, s48
	s_add_u32 s34, s34, 0x3e080
	s_addc_u32 s35, s35, 0
	s_add_u32 s51, s48, 0x100
	v_mov_b32_e32 v2, 0
	s_addc_u32 s52, s49, 0
	s_mov_b32 s53, -2
	s_add_u32 s2, s34, 0xfffc2080
	s_addc_u32 s3, s35, -1
	s_add_i32 s12, 0, 0x10000
	v_add_u32_e32 v110, s12, v179
	ds_read_b128 v[98:101], v110
	ds_read_b128 v[102:105], v110 offset:1024
	ds_read_b128 v[106:109], v110 offset:2048
	ds_read_b128 v[110:113], v110 offset:3072
	s_cmp_eq_u32 s53, 12
	s_cselect_b32 s49, s97, s3
	s_cselect_b32 s48, s96, s2
	s_cselect_b32 s3, s1, s52
	s_cselect_b32 s2, s23, s51
	v_lshl_add_u64 v[174:175], s[34:35], 0, v[170:171]
	s_add_i32 m0, s85, 0xc000
	ds_read_b128 v[114:117], v184
	ds_read_b128 v[118:121], v184 offset:1024
	ds_read_b128 v[122:125], v184 offset:2048
	ds_read_b128 v[126:129], v184 offset:3072
	ds_read_b128 v[186:189], v184 offset:4096
	ds_read_b128 v[190:193], v184 offset:5120
	ds_read_b128 v[194:197], v184 offset:6144
	ds_read_b128 v[198:201], v184 offset:7168
	global_load_lds_dwordx4 v[174:175], off
	v_lshl_add_u64 v[174:175], s[34:35], 0, v[172:173]
	s_add_i32 m0, s85, 0xe000
	s_nop 0
	global_load_lds_dwordx4 v[174:175], off
	s_waitcnt lgkmcnt(8)
	s_add_i32 s54, 0, 0x14000
	v_add_u32_e32 v174, s54, v179
	s_add_i32 s12, s12, s78
	ds_read_b128 v[226:229], v174
	ds_read_b128 v[230:233], v174 offset:1024
	ds_read_b128 v[234:237], v174 offset:2048
	ds_read_b128 v[242:245], v174 offset:3072
	s_nop 0
	s_waitcnt lgkmcnt(0)
	s_barrier
	s_waitcnt lgkmcnt(0)
	v_mfma_f32_16x16x32_bf16 v[158:161], v[98:101], v[114:117], 0
	v_mfma_f32_16x16x32_bf16 v[154:157], v[106:109], v[114:117], 0
	v_mfma_f32_16x16x32_bf16 v[150:153], v[98:101], v[122:125], 0
	v_mfma_f32_16x16x32_bf16 v[146:149], v[106:109], v[122:125], 0
	v_mfma_f32_16x16x32_bf16 v[142:145], v[98:101], v[186:189], 0
	v_mfma_f32_16x16x32_bf16 v[138:141], v[106:109], v[186:189], 0
	v_mfma_f32_16x16x32_bf16 v[134:137], v[98:101], v[194:197], 0
	v_mfma_f32_16x16x32_bf16 v[130:133], v[106:109], v[194:197], 0
	v_mfma_f32_16x16x32_bf16 v[158:161], v[102:105], v[118:121], v[158:161]
	v_mfma_f32_16x16x32_bf16 v[154:157], v[110:113], v[118:121], v[154:157]
	v_mfma_f32_16x16x32_bf16 v[150:153], v[102:105], v[126:129], v[150:153]
	v_mfma_f32_16x16x32_bf16 v[146:149], v[110:113], v[126:129], v[146:149]
	v_mfma_f32_16x16x32_bf16 v[142:145], v[102:105], v[190:193], v[142:145]
	v_mfma_f32_16x16x32_bf16 v[138:141], v[110:113], v[190:193], v[138:141]
	v_mfma_f32_16x16x32_bf16 v[134:137], v[102:105], v[198:201], v[134:137]
	v_mfma_f32_16x16x32_bf16 v[130:133], v[110:113], v[198:201], v[130:133]
	v_mfma_f32_16x16x32_bf16 v[62:65], v[226:229], v[114:117], 0
	v_mfma_f32_16x16x32_bf16 v[58:61], v[234:237], v[114:117], 0
	v_mfma_f32_16x16x32_bf16 v[54:57], v[226:229], v[122:125], 0
	v_mfma_f32_16x16x32_bf16 v[50:53], v[234:237], v[122:125], 0
	v_mfma_f32_16x16x32_bf16 v[46:49], v[226:229], v[186:189], 0
	v_mfma_f32_16x16x32_bf16 v[42:45], v[234:237], v[186:189], 0
	v_mfma_f32_16x16x32_bf16 v[38:41], v[226:229], v[194:197], 0
	v_mfma_f32_16x16x32_bf16 v[34:37], v[234:237], v[194:197], 0
	v_mfma_f32_16x16x32_bf16 v[62:65], v[230:233], v[118:121], v[62:65]
	v_mfma_f32_16x16x32_bf16 v[58:61], v[242:245], v[118:121], v[58:61]
	v_mfma_f32_16x16x32_bf16 v[54:57], v[230:233], v[126:129], v[54:57]
	v_mfma_f32_16x16x32_bf16 v[50:53], v[242:245], v[126:129], v[50:53]
	s_mov_b32 m0, s85
	v_lshl_add_u64 v[248:249], s[48:49], 0, v[162:163]
	v_mfma_f32_16x16x32_bf16 v[46:49], v[230:233], v[190:193], v[46:49]
	v_mfma_f32_16x16x32_bf16 v[42:45], v[242:245], v[190:193], v[42:45]
	v_mfma_f32_16x16x32_bf16 v[38:41], v[230:233], v[198:201], v[38:41]
	v_mfma_f32_16x16x32_bf16 v[34:37], v[242:245], v[198:201], v[34:37]
	s_barrier
	ds_read_b128 v[114:117], v184 offset:16384
	ds_read_b128 v[118:121], v184 offset:17408
	ds_read_b128 v[122:125], v184 offset:18432
	ds_read_b128 v[126:129], v184 offset:19456
	ds_read_b128 v[186:189], v184 offset:20480
	ds_read_b128 v[190:193], v184 offset:21504
	ds_read_b128 v[194:197], v184 offset:22528
	ds_read_b128 v[198:201], v184 offset:23552
	global_load_lds_dwordx4 v[248:249], off
	v_lshl_add_u64 v[250:251], s[48:49], 0, v[164:165]
	s_mov_b32 m0, s82
	s_nop 0
	global_load_lds_dwordx4 v[250:251], off
	v_lshl_add_u64 v[174:175], s[2:3], 0, v[0:1]
	s_mov_b32 m0, s12
	v_lshl_add_u64 v[246:247], s[2:3], 0, v[166:167]
	global_load_lds_dwordx4 v[174:175], off
	s_add_i32 m0, s12, 0x2000
	s_nop 0
	global_load_lds_dwordx4 v[246:247], off
	s_add_u32 s12, s2, 0x40000
	s_addc_u32 s13, s3, 0
	s_add_i32 s54, s54, s78
	v_lshl_add_u64 v[174:175], s[12:13], 0, v[0:1]
	s_mov_b32 m0, s54
	s_nop 0
	global_load_lds_dwordx4 v[174:175], off
	v_lshl_add_u64 v[174:175], s[12:13], 0, v[166:167]
	s_add_i32 m0, s54, 0x2000
	s_nop 0
	global_load_lds_dwordx4 v[174:175], off
	s_waitcnt vmcnt(6)
	s_nop 0
	s_waitcnt lgkmcnt(0)
	s_barrier
	s_waitcnt lgkmcnt(0)
	v_mfma_f32_16x16x32_bf16 v[94:97], v[98:101], v[114:117], 0
	v_mfma_f32_16x16x32_bf16 v[90:93], v[106:109], v[114:117], 0
	v_mfma_f32_16x16x32_bf16 v[86:89], v[98:101], v[122:125], 0
	v_mfma_f32_16x16x32_bf16 v[82:85], v[106:109], v[122:125], 0
	v_mfma_f32_16x16x32_bf16 v[78:81], v[98:101], v[186:189], 0
	v_mfma_f32_16x16x32_bf16 v[74:77], v[106:109], v[186:189], 0
	v_mfma_f32_16x16x32_bf16 v[70:73], v[98:101], v[194:197], 0
	v_mfma_f32_16x16x32_bf16 v[66:69], v[106:109], v[194:197], 0
	v_mfma_f32_16x16x32_bf16 v[94:97], v[102:105], v[118:121], v[94:97]
	v_mfma_f32_16x16x32_bf16 v[90:93], v[110:113], v[118:121], v[90:93]
	v_mfma_f32_16x16x32_bf16 v[86:89], v[102:105], v[126:129], v[86:89]
	v_mfma_f32_16x16x32_bf16 v[82:85], v[110:113], v[126:129], v[82:85]
	v_mfma_f32_16x16x32_bf16 v[78:81], v[102:105], v[190:193], v[78:81]
	v_mfma_f32_16x16x32_bf16 v[74:77], v[110:113], v[190:193], v[74:77]
	v_mfma_f32_16x16x32_bf16 v[70:73], v[102:105], v[198:201], v[70:73]
	v_mfma_f32_16x16x32_bf16 v[66:69], v[110:113], v[198:201], v[66:69]
	v_mfma_f32_16x16x32_bf16 v[30:33], v[226:229], v[114:117], 0
	v_mfma_f32_16x16x32_bf16 v[26:29], v[234:237], v[114:117], 0
	v_mfma_f32_16x16x32_bf16 v[22:25], v[226:229], v[122:125], 0
	v_mfma_f32_16x16x32_bf16 v[18:21], v[234:237], v[122:125], 0
	v_mfma_f32_16x16x32_bf16 v[14:17], v[226:229], v[186:189], 0
	v_mfma_f32_16x16x32_bf16 v[10:13], v[234:237], v[186:189], 0
	v_mfma_f32_16x16x32_bf16 v[6:9], v[226:229], v[194:197], 0
	v_mfma_f32_16x16x32_bf16 v[2:5], v[234:237], v[194:197], 0
	v_mfma_f32_16x16x32_bf16 v[30:33], v[230:233], v[118:121], v[30:33]
	v_mfma_f32_16x16x32_bf16 v[26:29], v[242:245], v[118:121], v[26:29]
	v_mfma_f32_16x16x32_bf16 v[22:25], v[230:233], v[126:129], v[22:25]
	v_mfma_f32_16x16x32_bf16 v[18:21], v[242:245], v[126:129], v[18:21]
	s_add_i32 s54, 0, 0x18000
	v_add_u32_e32 v110, s54, v179
	v_mfma_f32_16x16x32_bf16 v[14:17], v[230:233], v[190:193], v[14:17]
	v_mfma_f32_16x16x32_bf16 v[10:13], v[242:245], v[190:193], v[10:13]
	v_mfma_f32_16x16x32_bf16 v[6:9], v[230:233], v[198:201], v[6:9]
	v_mfma_f32_16x16x32_bf16 v[2:5], v[242:245], v[198:201], v[2:5]
	s_barrier
	ds_read_b128 v[98:101], v110
	ds_read_b128 v[102:105], v110 offset:1024
	ds_read_b128 v[106:109], v110 offset:2048
	ds_read_b128 v[110:113], v110 offset:3072
	s_add_u32 s12, s48, 0x3e000
	s_addc_u32 s13, s49, 0
	s_mov_b32 m0, s89
	v_lshl_add_u64 v[226:227], s[12:13], 0, v[162:163]
	ds_read_b128 v[114:117], v184 offset:32768
	ds_read_b128 v[118:121], v184 offset:33792
	ds_read_b128 v[122:125], v184 offset:34816
	ds_read_b128 v[126:129], v184 offset:35840
	ds_read_b128 v[186:189], v184 offset:36864
	ds_read_b128 v[190:193], v184 offset:37888
	ds_read_b128 v[194:197], v184 offset:38912
	ds_read_b128 v[198:201], v184 offset:39936
	global_load_lds_dwordx4 v[226:227], off
	v_lshl_add_u64 v[226:227], s[12:13], 0, v[164:165]
	s_mov_b32 m0, s91
	s_nop 0
	global_load_lds_dwordx4 v[226:227], off
	s_waitcnt lgkmcnt(8)
	s_add_i32 s12, 0, 0x1c000
	s_add_i32 s13, s54, s78
	v_add_u32_e32 v242, s12, v179
	ds_read_b128 v[226:229], v242
	ds_read_b128 v[230:233], v242 offset:1024
	ds_read_b128 v[234:237], v242 offset:2048
	ds_read_b128 v[242:245], v242 offset:3072
	s_nop 0
	s_waitcnt lgkmcnt(0)
	s_barrier
	s_waitcnt lgkmcnt(0)
	s_nop 0
	v_mfma_f32_16x16x32_bf16 v[158:161], v[98:101], v[114:117], v[158:161]
	v_mfma_f32_16x16x32_bf16 v[154:157], v[106:109], v[114:117], v[154:157]
	v_mfma_f32_16x16x32_bf16 v[150:153], v[98:101], v[122:125], v[150:153]
	v_mfma_f32_16x16x32_bf16 v[146:149], v[106:109], v[122:125], v[146:149]
	v_mfma_f32_16x16x32_bf16 v[142:145], v[98:101], v[186:189], v[142:145]
	v_mfma_f32_16x16x32_bf16 v[138:141], v[106:109], v[186:189], v[138:141]
	v_mfma_f32_16x16x32_bf16 v[134:137], v[98:101], v[194:197], v[134:137]
	v_mfma_f32_16x16x32_bf16 v[130:133], v[106:109], v[194:197], v[130:133]
	v_mfma_f32_16x16x32_bf16 v[158:161], v[102:105], v[118:121], v[158:161]
	v_mfma_f32_16x16x32_bf16 v[154:157], v[110:113], v[118:121], v[154:157]
	v_mfma_f32_16x16x32_bf16 v[150:153], v[102:105], v[126:129], v[150:153]
	v_mfma_f32_16x16x32_bf16 v[146:149], v[110:113], v[126:129], v[146:149]
	v_mfma_f32_16x16x32_bf16 v[142:145], v[102:105], v[190:193], v[142:145]
	v_mfma_f32_16x16x32_bf16 v[138:141], v[110:113], v[190:193], v[138:141]
	v_mfma_f32_16x16x32_bf16 v[134:137], v[102:105], v[198:201], v[134:137]
	v_mfma_f32_16x16x32_bf16 v[130:133], v[110:113], v[198:201], v[130:133]
	v_mfma_f32_16x16x32_bf16 v[62:65], v[226:229], v[114:117], v[62:65]
	v_mfma_f32_16x16x32_bf16 v[58:61], v[234:237], v[114:117], v[58:61]
	v_mfma_f32_16x16x32_bf16 v[54:57], v[226:229], v[122:125], v[54:57]
	v_mfma_f32_16x16x32_bf16 v[50:53], v[234:237], v[122:125], v[50:53]
	v_mfma_f32_16x16x32_bf16 v[46:49], v[226:229], v[186:189], v[46:49]
	v_mfma_f32_16x16x32_bf16 v[42:45], v[234:237], v[186:189], v[42:45]
	v_mfma_f32_16x16x32_bf16 v[38:41], v[226:229], v[194:197], v[38:41]
	v_mfma_f32_16x16x32_bf16 v[34:37], v[234:237], v[194:197], v[34:37]
	v_mfma_f32_16x16x32_bf16 v[62:65], v[230:233], v[118:121], v[62:65]
	v_mfma_f32_16x16x32_bf16 v[58:61], v[242:245], v[118:121], v[58:61]
	v_mfma_f32_16x16x32_bf16 v[54:57], v[230:233], v[126:129], v[54:57]
	v_mfma_f32_16x16x32_bf16 v[50:53], v[242:245], v[126:129], v[50:53]
	s_mov_b32 m0, s79
	v_lshl_add_u64 v[174:175], v[248:249], 0, s[20:21]
	v_mfma_f32_16x16x32_bf16 v[46:49], v[230:233], v[190:193], v[46:49]
	v_mfma_f32_16x16x32_bf16 v[42:45], v[242:245], v[190:193], v[42:45]
	v_mfma_f32_16x16x32_bf16 v[38:41], v[230:233], v[198:201], v[38:41]
	v_mfma_f32_16x16x32_bf16 v[34:37], v[242:245], v[198:201], v[34:37]
	s_barrier
	ds_read_b128 v[114:117], v184 offset:49152
	ds_read_b128 v[118:121], v184 offset:50176
	ds_read_b128 v[122:125], v184 offset:51200
	ds_read_b128 v[126:129], v184 offset:52224
	ds_read_b128 v[186:189], v184 offset:53248
	ds_read_b128 v[190:193], v184 offset:54272
	ds_read_b128 v[194:197], v184 offset:55296
	ds_read_b128 v[198:201], v184 offset:56320
	global_load_lds_dwordx4 v[174:175], off
	v_lshl_add_u64 v[174:175], v[250:251], 0, s[20:21]
	s_mov_b32 m0, s87
	s_nop 0
	global_load_lds_dwordx4 v[174:175], off
	v_lshl_add_u64 v[174:175], s[2:3], 0, v[0:1]
	v_lshl_add_u64 v[174:175], v[174:175], 0, s[20:21]
	s_mov_b32 m0, s13
	s_nop 0
	global_load_lds_dwordx4 v[174:175], off
	v_lshl_add_u64 v[174:175], v[246:247], 0, s[20:21]
	s_add_i32 m0, s13, 0x2000
	s_nop 0
	global_load_lds_dwordx4 v[174:175], off
	s_add_u32 s2, s2, 0x40080
	s_addc_u32 s3, s3, 0
	s_add_i32 s12, s12, s78
	v_lshl_add_u64 v[174:175], s[2:3], 0, v[0:1]
	s_mov_b32 m0, s12
	s_nop 0
	global_load_lds_dwordx4 v[174:175], off
	v_lshl_add_u64 v[174:175], s[2:3], 0, v[166:167]
	s_add_i32 m0, s12, 0x2000
	s_nop 0
	global_load_lds_dwordx4 v[174:175], off
	s_waitcnt vmcnt(6)
	s_nop 0
	s_waitcnt lgkmcnt(0)
	s_barrier
	s_waitcnt lgkmcnt(0)
	s_nop 0
	v_mfma_f32_16x16x32_bf16 v[94:97], v[98:101], v[114:117], v[94:97]
	v_mfma_f32_16x16x32_bf16 v[90:93], v[106:109], v[114:117], v[90:93]
	v_mfma_f32_16x16x32_bf16 v[86:89], v[98:101], v[122:125], v[86:89]
	v_mfma_f32_16x16x32_bf16 v[82:85], v[106:109], v[122:125], v[82:85]
	v_mfma_f32_16x16x32_bf16 v[78:81], v[98:101], v[186:189], v[78:81]
	v_mfma_f32_16x16x32_bf16 v[74:77], v[106:109], v[186:189], v[74:77]
	v_mfma_f32_16x16x32_bf16 v[70:73], v[98:101], v[194:197], v[70:73]
	v_mfma_f32_16x16x32_bf16 v[66:69], v[106:109], v[194:197], v[66:69]
	v_mfma_f32_16x16x32_bf16 v[94:97], v[102:105], v[118:121], v[94:97]
	v_mfma_f32_16x16x32_bf16 v[90:93], v[110:113], v[118:121], v[90:93]
	v_mfma_f32_16x16x32_bf16 v[86:89], v[102:105], v[126:129], v[86:89]
	v_mfma_f32_16x16x32_bf16 v[82:85], v[110:113], v[126:129], v[82:85]
	v_mfma_f32_16x16x32_bf16 v[78:81], v[102:105], v[190:193], v[78:81]
	v_mfma_f32_16x16x32_bf16 v[74:77], v[110:113], v[190:193], v[74:77]
	v_mfma_f32_16x16x32_bf16 v[70:73], v[102:105], v[198:201], v[70:73]
	v_mfma_f32_16x16x32_bf16 v[66:69], v[110:113], v[198:201], v[66:69]
	v_mfma_f32_16x16x32_bf16 v[30:33], v[226:229], v[114:117], v[30:33]
	v_mfma_f32_16x16x32_bf16 v[26:29], v[234:237], v[114:117], v[26:29]
	v_mfma_f32_16x16x32_bf16 v[22:25], v[226:229], v[122:125], v[22:25]
	v_mfma_f32_16x16x32_bf16 v[18:21], v[234:237], v[122:125], v[18:21]
	v_mfma_f32_16x16x32_bf16 v[14:17], v[226:229], v[186:189], v[14:17]
	v_mfma_f32_16x16x32_bf16 v[10:13], v[234:237], v[186:189], v[10:13]
	v_mfma_f32_16x16x32_bf16 v[6:9], v[226:229], v[194:197], v[6:9]
	v_mfma_f32_16x16x32_bf16 v[2:5], v[234:237], v[194:197], v[2:5]
	v_mfma_f32_16x16x32_bf16 v[30:33], v[230:233], v[118:121], v[30:33]
	v_mfma_f32_16x16x32_bf16 v[26:29], v[242:245], v[118:121], v[26:29]
	v_mfma_f32_16x16x32_bf16 v[22:25], v[230:233], v[126:129], v[22:25]
	v_mfma_f32_16x16x32_bf16 v[18:21], v[242:245], v[126:129], v[18:21]
	s_add_i32 s53, s53, 2
	s_add_u32 s34, s34, 0x100
	s_addc_u32 s35, s35, 0
	s_add_u32 s51, s51, 0x100
	s_addc_u32 s52, s52, 0
	s_cmp_gt_u32 s53, 13
	v_mfma_f32_16x16x32_bf16 v[14:17], v[230:233], v[190:193], v[14:17]
	v_mfma_f32_16x16x32_bf16 v[10:13], v[242:245], v[190:193], v[10:13]
	v_mfma_f32_16x16x32_bf16 v[6:9], v[230:233], v[198:201], v[6:9]
	v_mfma_f32_16x16x32_bf16 v[2:5], v[242:245], v[198:201], v[2:5]
	s_barrier
	s_cbranch_scc1 .Lpeel_x_0
.LBB0_104:
	s_add_u32 s2, s34, 0xfffc2080
	s_addc_u32 s3, s35, -1
	s_add_i32 s12, 0, 0x10000
	v_add_u32_e32 v110, s12, v179
	ds_read_b128 v[98:101], v110
	ds_read_b128 v[102:105], v110 offset:1024
	ds_read_b128 v[106:109], v110 offset:2048
	ds_read_b128 v[110:113], v110 offset:3072
	s_cmp_eq_u32 s53, 12
	s_cselect_b32 s49, s97, s3
	s_cselect_b32 s48, s96, s2
	s_cselect_b32 s3, s1, s52
	s_cselect_b32 s2, s23, s51
	v_lshl_add_u64 v[174:175], s[34:35], 0, v[170:171]
	s_add_i32 m0, s85, 0xc000
	ds_read_b128 v[114:117], v184
	ds_read_b128 v[118:121], v184 offset:1024
	ds_read_b128 v[122:125], v184 offset:2048
	ds_read_b128 v[126:129], v184 offset:3072
	ds_read_b128 v[186:189], v184 offset:4096
	ds_read_b128 v[190:193], v184 offset:5120
	ds_read_b128 v[194:197], v184 offset:6144
	ds_read_b128 v[198:201], v184 offset:7168
	global_load_lds_dwordx4 v[174:175], off
	v_lshl_add_u64 v[174:175], s[34:35], 0, v[172:173]
	s_add_i32 m0, s85, 0xe000
	s_nop 0
	global_load_lds_dwordx4 v[174:175], off
	s_waitcnt lgkmcnt(8)
	s_add_i32 s54, 0, 0x14000
	v_add_u32_e32 v174, s54, v179
	s_add_i32 s12, s12, s78
	ds_read_b128 v[226:229], v174
	ds_read_b128 v[230:233], v174 offset:1024
	ds_read_b128 v[234:237], v174 offset:2048
	ds_read_b128 v[242:245], v174 offset:3072
	s_nop 0
	s_waitcnt lgkmcnt(0)
	s_barrier
	s_waitcnt lgkmcnt(0)
	s_nop 0
	v_mfma_f32_16x16x32_bf16 v[158:161], v[98:101], v[114:117], v[158:161]
	v_mfma_f32_16x16x32_bf16 v[154:157], v[106:109], v[114:117], v[154:157]
	v_mfma_f32_16x16x32_bf16 v[150:153], v[98:101], v[122:125], v[150:153]
	v_mfma_f32_16x16x32_bf16 v[146:149], v[106:109], v[122:125], v[146:149]
	v_mfma_f32_16x16x32_bf16 v[142:145], v[98:101], v[186:189], v[142:145]
	v_mfma_f32_16x16x32_bf16 v[138:141], v[106:109], v[186:189], v[138:141]
	v_mfma_f32_16x16x32_bf16 v[134:137], v[98:101], v[194:197], v[134:137]
	v_mfma_f32_16x16x32_bf16 v[130:133], v[106:109], v[194:197], v[130:133]
	v_mfma_f32_16x16x32_bf16 v[158:161], v[102:105], v[118:121], v[158:161]
	v_mfma_f32_16x16x32_bf16 v[154:157], v[110:113], v[118:121], v[154:157]
	v_mfma_f32_16x16x32_bf16 v[150:153], v[102:105], v[126:129], v[150:153]
	v_mfma_f32_16x16x32_bf16 v[146:149], v[110:113], v[126:129], v[146:149]
	v_mfma_f32_16x16x32_bf16 v[142:145], v[102:105], v[190:193], v[142:145]
	v_mfma_f32_16x16x32_bf16 v[138:141], v[110:113], v[190:193], v[138:141]
	v_mfma_f32_16x16x32_bf16 v[134:137], v[102:105], v[198:201], v[134:137]
	v_mfma_f32_16x16x32_bf16 v[130:133], v[110:113], v[198:201], v[130:133]
	v_mfma_f32_16x16x32_bf16 v[62:65], v[226:229], v[114:117], v[62:65]
	v_mfma_f32_16x16x32_bf16 v[58:61], v[234:237], v[114:117], v[58:61]
	v_mfma_f32_16x16x32_bf16 v[54:57], v[226:229], v[122:125], v[54:57]
	v_mfma_f32_16x16x32_bf16 v[50:53], v[234:237], v[122:125], v[50:53]
	v_mfma_f32_16x16x32_bf16 v[46:49], v[226:229], v[186:189], v[46:49]
	v_mfma_f32_16x16x32_bf16 v[42:45], v[234:237], v[186:189], v[42:45]
	v_mfma_f32_16x16x32_bf16 v[38:41], v[226:229], v[194:197], v[38:41]
	v_mfma_f32_16x16x32_bf16 v[34:37], v[234:237], v[194:197], v[34:37]
	v_mfma_f32_16x16x32_bf16 v[62:65], v[230:233], v[118:121], v[62:65]
	v_mfma_f32_16x16x32_bf16 v[58:61], v[242:245], v[118:121], v[58:61]
	v_mfma_f32_16x16x32_bf16 v[54:57], v[230:233], v[126:129], v[54:57]
	v_mfma_f32_16x16x32_bf16 v[50:53], v[242:245], v[126:129], v[50:53]
	s_mov_b32 m0, s85
	v_lshl_add_u64 v[248:249], s[48:49], 0, v[162:163]
	v_mfma_f32_16x16x32_bf16 v[46:49], v[230:233], v[190:193], v[46:49]
	v_mfma_f32_16x16x32_bf16 v[42:45], v[242:245], v[190:193], v[42:45]
	v_mfma_f32_16x16x32_bf16 v[38:41], v[230:233], v[198:201], v[38:41]
	v_mfma_f32_16x16x32_bf16 v[34:37], v[242:245], v[198:201], v[34:37]
	s_barrier
	ds_read_b128 v[114:117], v184 offset:16384
	ds_read_b128 v[118:121], v184 offset:17408
	ds_read_b128 v[122:125], v184 offset:18432
	ds_read_b128 v[126:129], v184 offset:19456
	ds_read_b128 v[186:189], v184 offset:20480
	ds_read_b128 v[190:193], v184 offset:21504
	ds_read_b128 v[194:197], v184 offset:22528
	ds_read_b128 v[198:201], v184 offset:23552
	global_load_lds_dwordx4 v[248:249], off
	v_lshl_add_u64 v[250:251], s[48:49], 0, v[164:165]
	s_mov_b32 m0, s82
	s_nop 0
	global_load_lds_dwordx4 v[250:251], off
	v_lshl_add_u64 v[174:175], s[2:3], 0, v[0:1]
	s_mov_b32 m0, s12
	v_lshl_add_u64 v[246:247], s[2:3], 0, v[166:167]
	global_load_lds_dwordx4 v[174:175], off
	s_add_i32 m0, s12, 0x2000
	s_nop 0
	global_load_lds_dwordx4 v[246:247], off
	s_add_u32 s12, s2, 0x40000
	s_addc_u32 s13, s3, 0
	s_add_i32 s54, s54, s78
	v_lshl_add_u64 v[174:175], s[12:13], 0, v[0:1]
	s_mov_b32 m0, s54
	s_nop 0
	global_load_lds_dwordx4 v[174:175], off
	v_lshl_add_u64 v[174:175], s[12:13], 0, v[166:167]
	s_add_i32 m0, s54, 0x2000
	s_nop 0
	global_load_lds_dwordx4 v[174:175], off
	s_waitcnt vmcnt(6)
	s_nop 0
	s_waitcnt lgkmcnt(0)
	s_barrier
	s_waitcnt lgkmcnt(0)
	v_mfma_f32_16x16x32_bf16 v[94:97], v[98:101], v[114:117], v[94:97]
	v_mfma_f32_16x16x32_bf16 v[90:93], v[106:109], v[114:117], v[90:93]
	v_mfma_f32_16x16x32_bf16 v[86:89], v[98:101], v[122:125], v[86:89]
	v_mfma_f32_16x16x32_bf16 v[82:85], v[106:109], v[122:125], v[82:85]
	v_mfma_f32_16x16x32_bf16 v[78:81], v[98:101], v[186:189], v[78:81]
	v_mfma_f32_16x16x32_bf16 v[74:77], v[106:109], v[186:189], v[74:77]
	v_mfma_f32_16x16x32_bf16 v[70:73], v[98:101], v[194:197], v[70:73]
	v_mfma_f32_16x16x32_bf16 v[66:69], v[106:109], v[194:197], v[66:69]
	v_mfma_f32_16x16x32_bf16 v[94:97], v[102:105], v[118:121], v[94:97]
	v_mfma_f32_16x16x32_bf16 v[90:93], v[110:113], v[118:121], v[90:93]
	v_mfma_f32_16x16x32_bf16 v[86:89], v[102:105], v[126:129], v[86:89]
	v_mfma_f32_16x16x32_bf16 v[82:85], v[110:113], v[126:129], v[82:85]
	v_mfma_f32_16x16x32_bf16 v[78:81], v[102:105], v[190:193], v[78:81]
	v_mfma_f32_16x16x32_bf16 v[74:77], v[110:113], v[190:193], v[74:77]
	v_mfma_f32_16x16x32_bf16 v[70:73], v[102:105], v[198:201], v[70:73]
	v_mfma_f32_16x16x32_bf16 v[66:69], v[110:113], v[198:201], v[66:69]
	v_mfma_f32_16x16x32_bf16 v[30:33], v[226:229], v[114:117], v[30:33]
	v_mfma_f32_16x16x32_bf16 v[26:29], v[234:237], v[114:117], v[26:29]
	v_mfma_f32_16x16x32_bf16 v[22:25], v[226:229], v[122:125], v[22:25]
	v_mfma_f32_16x16x32_bf16 v[18:21], v[234:237], v[122:125], v[18:21]
	v_mfma_f32_16x16x32_bf16 v[14:17], v[226:229], v[186:189], v[14:17]
	v_mfma_f32_16x16x32_bf16 v[10:13], v[234:237], v[186:189], v[10:13]
	v_mfma_f32_16x16x32_bf16 v[6:9], v[226:229], v[194:197], v[6:9]
	v_mfma_f32_16x16x32_bf16 v[2:5], v[234:237], v[194:197], v[2:5]
	v_mfma_f32_16x16x32_bf16 v[30:33], v[230:233], v[118:121], v[30:33]
	v_mfma_f32_16x16x32_bf16 v[26:29], v[242:245], v[118:121], v[26:29]
	v_mfma_f32_16x16x32_bf16 v[22:25], v[230:233], v[126:129], v[22:25]
	v_mfma_f32_16x16x32_bf16 v[18:21], v[242:245], v[126:129], v[18:21]
	s_add_i32 s54, 0, 0x18000
	v_add_u32_e32 v110, s54, v179
	v_mfma_f32_16x16x32_bf16 v[14:17], v[230:233], v[190:193], v[14:17]
	v_mfma_f32_16x16x32_bf16 v[10:13], v[242:245], v[190:193], v[10:13]
	v_mfma_f32_16x16x32_bf16 v[6:9], v[230:233], v[198:201], v[6:9]
	v_mfma_f32_16x16x32_bf16 v[2:5], v[242:245], v[198:201], v[2:5]
	s_barrier
	ds_read_b128 v[98:101], v110
	ds_read_b128 v[102:105], v110 offset:1024
	ds_read_b128 v[106:109], v110 offset:2048
	ds_read_b128 v[110:113], v110 offset:3072
	s_add_u32 s12, s48, 0x3e000
	s_addc_u32 s13, s49, 0
	s_mov_b32 m0, s89
	v_lshl_add_u64 v[226:227], s[12:13], 0, v[162:163]
	ds_read_b128 v[114:117], v184 offset:32768
	ds_read_b128 v[118:121], v184 offset:33792
	ds_read_b128 v[122:125], v184 offset:34816
	ds_read_b128 v[126:129], v184 offset:35840
	ds_read_b128 v[186:189], v184 offset:36864
	ds_read_b128 v[190:193], v184 offset:37888
	ds_read_b128 v[194:197], v184 offset:38912
	ds_read_b128 v[198:201], v184 offset:39936
	global_load_lds_dwordx4 v[226:227], off
	v_lshl_add_u64 v[226:227], s[12:13], 0, v[164:165]
	s_mov_b32 m0, s91
	s_nop 0
	global_load_lds_dwordx4 v[226:227], off
	s_waitcnt lgkmcnt(8)
	s_add_i32 s12, 0, 0x1c000
	s_add_i32 s13, s54, s78
	v_add_u32_e32 v242, s12, v179
	ds_read_b128 v[226:229], v242
	ds_read_b128 v[230:233], v242 offset:1024
	ds_read_b128 v[234:237], v242 offset:2048
	ds_read_b128 v[242:245], v242 offset:3072
	s_nop 0
	s_waitcnt lgkmcnt(0)
	s_barrier
	s_waitcnt lgkmcnt(0)
	s_nop 0
	v_mfma_f32_16x16x32_bf16 v[158:161], v[98:101], v[114:117], v[158:161]
	v_mfma_f32_16x16x32_bf16 v[154:157], v[106:109], v[114:117], v[154:157]
	v_mfma_f32_16x16x32_bf16 v[150:153], v[98:101], v[122:125], v[150:153]
	v_mfma_f32_16x16x32_bf16 v[146:149], v[106:109], v[122:125], v[146:149]
	v_mfma_f32_16x16x32_bf16 v[142:145], v[98:101], v[186:189], v[142:145]
	v_mfma_f32_16x16x32_bf16 v[138:141], v[106:109], v[186:189], v[138:141]
	v_mfma_f32_16x16x32_bf16 v[134:137], v[98:101], v[194:197], v[134:137]
	v_mfma_f32_16x16x32_bf16 v[130:133], v[106:109], v[194:197], v[130:133]
	v_mfma_f32_16x16x32_bf16 v[158:161], v[102:105], v[118:121], v[158:161]
	v_mfma_f32_16x16x32_bf16 v[154:157], v[110:113], v[118:121], v[154:157]
	v_mfma_f32_16x16x32_bf16 v[150:153], v[102:105], v[126:129], v[150:153]
	v_mfma_f32_16x16x32_bf16 v[146:149], v[110:113], v[126:129], v[146:149]
	v_mfma_f32_16x16x32_bf16 v[142:145], v[102:105], v[190:193], v[142:145]
	v_mfma_f32_16x16x32_bf16 v[138:141], v[110:113], v[190:193], v[138:141]
	v_mfma_f32_16x16x32_bf16 v[134:137], v[102:105], v[198:201], v[134:137]
	v_mfma_f32_16x16x32_bf16 v[130:133], v[110:113], v[198:201], v[130:133]
	v_mfma_f32_16x16x32_bf16 v[62:65], v[226:229], v[114:117], v[62:65]
	v_mfma_f32_16x16x32_bf16 v[58:61], v[234:237], v[114:117], v[58:61]
	v_mfma_f32_16x16x32_bf16 v[54:57], v[226:229], v[122:125], v[54:57]
	v_mfma_f32_16x16x32_bf16 v[50:53], v[234:237], v[122:125], v[50:53]
	v_mfma_f32_16x16x32_bf16 v[46:49], v[226:229], v[186:189], v[46:49]
	v_mfma_f32_16x16x32_bf16 v[42:45], v[234:237], v[186:189], v[42:45]
	v_mfma_f32_16x16x32_bf16 v[38:41], v[226:229], v[194:197], v[38:41]
	v_mfma_f32_16x16x32_bf16 v[34:37], v[234:237], v[194:197], v[34:37]
	v_mfma_f32_16x16x32_bf16 v[62:65], v[230:233], v[118:121], v[62:65]
	v_mfma_f32_16x16x32_bf16 v[58:61], v[242:245], v[118:121], v[58:61]
	v_mfma_f32_16x16x32_bf16 v[54:57], v[230:233], v[126:129], v[54:57]
	v_mfma_f32_16x16x32_bf16 v[50:53], v[242:245], v[126:129], v[50:53]
	s_mov_b32 m0, s79
	v_lshl_add_u64 v[174:175], v[248:249], 0, s[20:21]
	v_mfma_f32_16x16x32_bf16 v[46:49], v[230:233], v[190:193], v[46:49]
	v_mfma_f32_16x16x32_bf16 v[42:45], v[242:245], v[190:193], v[42:45]
	v_mfma_f32_16x16x32_bf16 v[38:41], v[230:233], v[198:201], v[38:41]
	v_mfma_f32_16x16x32_bf16 v[34:37], v[242:245], v[198:201], v[34:37]
	s_barrier
	ds_read_b128 v[114:117], v184 offset:49152
	ds_read_b128 v[118:121], v184 offset:50176
	ds_read_b128 v[122:125], v184 offset:51200
	ds_read_b128 v[126:129], v184 offset:52224
	ds_read_b128 v[186:189], v184 offset:53248
	ds_read_b128 v[190:193], v184 offset:54272
	ds_read_b128 v[194:197], v184 offset:55296
	ds_read_b128 v[198:201], v184 offset:56320
	global_load_lds_dwordx4 v[174:175], off
	v_lshl_add_u64 v[174:175], v[250:251], 0, s[20:21]
	s_mov_b32 m0, s87
	s_nop 0
	global_load_lds_dwordx4 v[174:175], off
	v_lshl_add_u64 v[174:175], s[2:3], 0, v[0:1]
	v_lshl_add_u64 v[174:175], v[174:175], 0, s[20:21]
	s_mov_b32 m0, s13
	s_nop 0
	global_load_lds_dwordx4 v[174:175], off
	v_lshl_add_u64 v[174:175], v[246:247], 0, s[20:21]
	s_add_i32 m0, s13, 0x2000
	s_nop 0
	global_load_lds_dwordx4 v[174:175], off
	s_add_u32 s2, s2, 0x40080
	s_addc_u32 s3, s3, 0
	s_add_i32 s12, s12, s78
	v_lshl_add_u64 v[174:175], s[2:3], 0, v[0:1]
	s_mov_b32 m0, s12
	s_nop 0
	global_load_lds_dwordx4 v[174:175], off
	v_lshl_add_u64 v[174:175], s[2:3], 0, v[166:167]
	s_add_i32 m0, s12, 0x2000
	s_nop 0
	global_load_lds_dwordx4 v[174:175], off
	s_waitcnt vmcnt(6)
	s_nop 0
	s_waitcnt lgkmcnt(0)
	s_barrier
	s_waitcnt lgkmcnt(0)
	s_nop 0
	v_mfma_f32_16x16x32_bf16 v[94:97], v[98:101], v[114:117], v[94:97]
	v_mfma_f32_16x16x32_bf16 v[90:93], v[106:109], v[114:117], v[90:93]
	v_mfma_f32_16x16x32_bf16 v[86:89], v[98:101], v[122:125], v[86:89]
	v_mfma_f32_16x16x32_bf16 v[82:85], v[106:109], v[122:125], v[82:85]
	v_mfma_f32_16x16x32_bf16 v[78:81], v[98:101], v[186:189], v[78:81]
	v_mfma_f32_16x16x32_bf16 v[74:77], v[106:109], v[186:189], v[74:77]
	v_mfma_f32_16x16x32_bf16 v[70:73], v[98:101], v[194:197], v[70:73]
	v_mfma_f32_16x16x32_bf16 v[66:69], v[106:109], v[194:197], v[66:69]
	v_mfma_f32_16x16x32_bf16 v[94:97], v[102:105], v[118:121], v[94:97]
	v_mfma_f32_16x16x32_bf16 v[90:93], v[110:113], v[118:121], v[90:93]
	v_mfma_f32_16x16x32_bf16 v[86:89], v[102:105], v[126:129], v[86:89]
	v_mfma_f32_16x16x32_bf16 v[82:85], v[110:113], v[126:129], v[82:85]
	v_mfma_f32_16x16x32_bf16 v[78:81], v[102:105], v[190:193], v[78:81]
	v_mfma_f32_16x16x32_bf16 v[74:77], v[110:113], v[190:193], v[74:77]
	v_mfma_f32_16x16x32_bf16 v[70:73], v[102:105], v[198:201], v[70:73]
	v_mfma_f32_16x16x32_bf16 v[66:69], v[110:113], v[198:201], v[66:69]
	v_mfma_f32_16x16x32_bf16 v[30:33], v[226:229], v[114:117], v[30:33]
	v_mfma_f32_16x16x32_bf16 v[26:29], v[234:237], v[114:117], v[26:29]
	v_mfma_f32_16x16x32_bf16 v[22:25], v[226:229], v[122:125], v[22:25]
	v_mfma_f32_16x16x32_bf16 v[18:21], v[234:237], v[122:125], v[18:21]
	v_mfma_f32_16x16x32_bf16 v[14:17], v[226:229], v[186:189], v[14:17]
	v_mfma_f32_16x16x32_bf16 v[10:13], v[234:237], v[186:189], v[10:13]
	v_mfma_f32_16x16x32_bf16 v[6:9], v[226:229], v[194:197], v[6:9]
	v_mfma_f32_16x16x32_bf16 v[2:5], v[234:237], v[194:197], v[2:5]
	v_mfma_f32_16x16x32_bf16 v[30:33], v[230:233], v[118:121], v[30:33]
	v_mfma_f32_16x16x32_bf16 v[26:29], v[242:245], v[118:121], v[26:29]
	v_mfma_f32_16x16x32_bf16 v[22:25], v[230:233], v[126:129], v[22:25]
	v_mfma_f32_16x16x32_bf16 v[18:21], v[242:245], v[126:129], v[18:21]
	s_add_i32 s53, s53, 2
	s_add_u32 s34, s34, 0x100
	s_addc_u32 s35, s35, 0
	s_add_u32 s51, s51, 0x100
	s_addc_u32 s52, s52, 0
	s_cmp_gt_u32 s53, 13
	v_mfma_f32_16x16x32_bf16 v[14:17], v[230:233], v[190:193], v[14:17]
	v_mfma_f32_16x16x32_bf16 v[10:13], v[242:245], v[190:193], v[10:13]
	v_mfma_f32_16x16x32_bf16 v[6:9], v[230:233], v[198:201], v[6:9]
	v_mfma_f32_16x16x32_bf16 v[2:5], v[242:245], v[198:201], v[2:5]
	s_barrier
	s_cbranch_scc0 .LBB0_104

.LBB0_181:
	s_add_i32 s88, s44, -2
	s_add_u32 s34, s34, 0x80
	s_addc_u32 s35, s35, 0
	s_add_u32 s89, s42, 0x100
	v_mov_b32_e32 v2, 0
	s_addc_u32 s90, s43, 0
	s_mov_b32 s2, 0
	s_add_i32 s91, s2, 2
	s_add_u32 s12, s34, 0x80
	s_addc_u32 s3, s35, 0
	s_add_i32 s13, 0, 0x10000
	v_add_u32_e32 v142, s13, v183
	ds_read_b128 v[130:133], v142
	ds_read_b128 v[134:137], v142 offset:1024
	ds_read_b128 v[138:141], v142 offset:2048
	ds_read_b128 v[142:145], v142 offset:3072
	s_cmp_eq_u32 s88, s2
	s_cselect_b32 s2, s0, s12
	s_cselect_b32 s3, s1, s3
	s_cselect_b32 s43, s41, s90
	s_cselect_b32 s42, s40, s89
	v_lshl_add_u64 v[190:191], s[34:35], 0, v[174:175]
	s_add_i32 m0, s55, 0xc000
	ds_read_b128 v[146:149], v184
	ds_read_b128 v[150:153], v184 offset:1024
	ds_read_b128 v[154:157], v184 offset:2048
	ds_read_b128 v[158:161], v184 offset:3072
	ds_read_b128 v[162:165], v184 offset:4096
	ds_read_b128 v[166:169], v184 offset:5120
	ds_read_b128 v[178:181], v184 offset:6144
	ds_read_b128 v[186:189], v184 offset:7168
	global_load_lds_dwordx4 v[190:191], off
	v_lshl_add_u64 v[190:191], s[34:35], 0, v[176:177]
	s_add_i32 m0, s55, 0xe000
	s_nop 0
	global_load_lds_dwordx4 v[190:191], off
	s_waitcnt lgkmcnt(8)
	s_add_i32 s92, 0, 0x14000
	s_add_i32 s12, s13, s54
	v_add_u32_e32 v185, s92, v183
	ds_read_b128 v[190:193], v185
	ds_read_b128 v[194:197], v185 offset:1024
	ds_read_b128 v[198:201], v185 offset:2048
	ds_read_b128 v[226:229], v185 offset:3072
	s_nop 0
	s_waitcnt lgkmcnt(0)
	s_barrier
	s_waitcnt lgkmcnt(0)
	v_mfma_f32_16x16x32_bf16 v[126:129], v[130:133], v[146:149], 0
	v_mfma_f32_16x16x32_bf16 v[122:125], v[138:141], v[146:149], 0
	v_mfma_f32_16x16x32_bf16 v[118:121], v[130:133], v[154:157], 0
	v_mfma_f32_16x16x32_bf16 v[114:117], v[138:141], v[154:157], 0
	v_mfma_f32_16x16x32_bf16 v[110:113], v[130:133], v[162:165], 0
	v_mfma_f32_16x16x32_bf16 v[106:109], v[138:141], v[162:165], 0
	v_mfma_f32_16x16x32_bf16 v[102:105], v[130:133], v[178:181], 0
	v_mfma_f32_16x16x32_bf16 v[98:101], v[138:141], v[178:181], 0
	v_mfma_f32_16x16x32_bf16 v[126:129], v[134:137], v[150:153], v[126:129]
	v_mfma_f32_16x16x32_bf16 v[122:125], v[142:145], v[150:153], v[122:125]
	v_mfma_f32_16x16x32_bf16 v[118:121], v[134:137], v[158:161], v[118:121]
	v_mfma_f32_16x16x32_bf16 v[114:117], v[142:145], v[158:161], v[114:117]
	v_mfma_f32_16x16x32_bf16 v[110:113], v[134:137], v[166:169], v[110:113]
	v_mfma_f32_16x16x32_bf16 v[106:109], v[142:145], v[166:169], v[106:109]
	v_mfma_f32_16x16x32_bf16 v[102:105], v[134:137], v[186:189], v[102:105]
	v_mfma_f32_16x16x32_bf16 v[98:101], v[142:145], v[186:189], v[98:101]
	v_mfma_f32_16x16x32_bf16 v[62:65], v[190:193], v[146:149], 0
	v_mfma_f32_16x16x32_bf16 v[58:61], v[198:201], v[146:149], 0
	v_mfma_f32_16x16x32_bf16 v[54:57], v[190:193], v[154:157], 0
	v_mfma_f32_16x16x32_bf16 v[50:53], v[198:201], v[154:157], 0
	v_mfma_f32_16x16x32_bf16 v[46:49], v[190:193], v[162:165], 0
	v_mfma_f32_16x16x32_bf16 v[42:45], v[198:201], v[162:165], 0
	v_mfma_f32_16x16x32_bf16 v[38:41], v[190:193], v[178:181], 0
	v_mfma_f32_16x16x32_bf16 v[34:37], v[198:201], v[178:181], 0
	v_mfma_f32_16x16x32_bf16 v[62:65], v[194:197], v[150:153], v[62:65]
	v_mfma_f32_16x16x32_bf16 v[58:61], v[226:229], v[150:153], v[58:61]
	v_mfma_f32_16x16x32_bf16 v[54:57], v[194:197], v[158:161], v[54:57]
	v_mfma_f32_16x16x32_bf16 v[50:53], v[226:229], v[158:161], v[50:53]
	s_mov_b32 m0, s55
	v_lshl_add_u64 v[234:235], s[2:3], 0, v[170:171]
	v_mfma_f32_16x16x32_bf16 v[46:49], v[194:197], v[166:169], v[46:49]
	v_mfma_f32_16x16x32_bf16 v[42:45], v[226:229], v[166:169], v[42:45]
	v_mfma_f32_16x16x32_bf16 v[38:41], v[194:197], v[186:189], v[38:41]
	v_mfma_f32_16x16x32_bf16 v[34:37], v[226:229], v[186:189], v[34:37]
	s_barrier
	ds_read_b128 v[146:149], v184 offset:16384
	ds_read_b128 v[150:153], v184 offset:17408
	ds_read_b128 v[154:157], v184 offset:18432
	ds_read_b128 v[158:161], v184 offset:19456
	ds_read_b128 v[162:165], v184 offset:20480
	ds_read_b128 v[166:169], v184 offset:21504
	ds_read_b128 v[178:181], v184 offset:22528
	ds_read_b128 v[186:189], v184 offset:23552
	global_load_lds_dwordx4 v[234:235], off
	v_lshl_add_u64 v[236:237], s[2:3], 0, v[172:173]
	s_mov_b32 m0, s58
	s_nop 0
	global_load_lds_dwordx4 v[236:237], off
	v_lshl_add_u64 v[230:231], s[42:43], 0, v[170:171]
	s_mov_b32 m0, s12
	s_nop 0
	global_load_lds_dwordx4 v[230:231], off
	v_lshl_add_u64 v[232:233], s[42:43], 0, v[172:173]
	s_add_i32 m0, s12, 0x2000
	s_nop 0
	global_load_lds_dwordx4 v[232:233], off
	s_add_u32 s12, s42, s18
	s_addc_u32 s13, s43, 0
	s_add_i32 s42, s92, s54
	v_lshl_add_u64 v[242:243], s[12:13], 0, v[170:171]
	s_mov_b32 m0, s42
	v_lshl_add_u64 v[244:245], s[12:13], 0, v[172:173]
	global_load_lds_dwordx4 v[242:243], off
	s_add_i32 m0, s42, 0x2000
	s_nop 0
	global_load_lds_dwordx4 v[244:245], off
	s_waitcnt vmcnt(6)
	s_nop 0
	s_waitcnt lgkmcnt(0)
	s_barrier
	s_waitcnt lgkmcnt(0)
	s_nop 0
	v_mfma_f32_16x16x32_bf16 v[94:97], v[130:133], v[146:149], 0
	v_mfma_f32_16x16x32_bf16 v[90:93], v[138:141], v[146:149], 0
	v_mfma_f32_16x16x32_bf16 v[86:89], v[130:133], v[154:157], 0
	v_mfma_f32_16x16x32_bf16 v[82:85], v[138:141], v[154:157], 0
	v_mfma_f32_16x16x32_bf16 v[78:81], v[130:133], v[162:165], 0
	v_mfma_f32_16x16x32_bf16 v[74:77], v[138:141], v[162:165], 0
	v_mfma_f32_16x16x32_bf16 v[70:73], v[130:133], v[178:181], 0
	v_mfma_f32_16x16x32_bf16 v[66:69], v[138:141], v[178:181], 0
	v_mfma_f32_16x16x32_bf16 v[94:97], v[134:137], v[150:153], v[94:97]
	v_mfma_f32_16x16x32_bf16 v[90:93], v[142:145], v[150:153], v[90:93]
	v_mfma_f32_16x16x32_bf16 v[86:89], v[134:137], v[158:161], v[86:89]
	v_mfma_f32_16x16x32_bf16 v[82:85], v[142:145], v[158:161], v[82:85]
	v_mfma_f32_16x16x32_bf16 v[78:81], v[134:137], v[166:169], v[78:81]
	v_mfma_f32_16x16x32_bf16 v[74:77], v[142:145], v[166:169], v[74:77]
	v_mfma_f32_16x16x32_bf16 v[70:73], v[134:137], v[186:189], v[70:73]
	v_mfma_f32_16x16x32_bf16 v[66:69], v[142:145], v[186:189], v[66:69]
	v_mfma_f32_16x16x32_bf16 v[30:33], v[190:193], v[146:149], 0
	v_mfma_f32_16x16x32_bf16 v[26:29], v[198:201], v[146:149], 0
	v_mfma_f32_16x16x32_bf16 v[22:25], v[190:193], v[154:157], 0
	v_mfma_f32_16x16x32_bf16 v[18:21], v[198:201], v[154:157], 0
	v_mfma_f32_16x16x32_bf16 v[14:17], v[190:193], v[162:165], 0
	v_mfma_f32_16x16x32_bf16 v[10:13], v[198:201], v[162:165], 0
	v_mfma_f32_16x16x32_bf16 v[6:9], v[190:193], v[178:181], 0
	v_mfma_f32_16x16x32_bf16 v[2:5], v[198:201], v[178:181], 0
	v_mfma_f32_16x16x32_bf16 v[30:33], v[194:197], v[150:153], v[30:33]
	v_mfma_f32_16x16x32_bf16 v[26:29], v[226:229], v[150:153], v[26:29]
	v_mfma_f32_16x16x32_bf16 v[22:25], v[194:197], v[158:161], v[22:25]
	v_mfma_f32_16x16x32_bf16 v[18:21], v[226:229], v[158:161], v[18:21]
	s_add_i32 s12, 0, 0x18000
	v_add_u32_e32 v142, s12, v183
	v_mfma_f32_16x16x32_bf16 v[14:17], v[194:197], v[166:169], v[14:17]
	v_mfma_f32_16x16x32_bf16 v[10:13], v[226:229], v[166:169], v[10:13]
	v_mfma_f32_16x16x32_bf16 v[6:9], v[194:197], v[186:189], v[6:9]
	v_mfma_f32_16x16x32_bf16 v[2:5], v[226:229], v[186:189], v[2:5]
	s_barrier
	ds_read_b128 v[130:133], v142
	ds_read_b128 v[134:137], v142 offset:1024
	ds_read_b128 v[138:141], v142 offset:2048
	ds_read_b128 v[142:145], v142 offset:3072
	s_add_u32 s2, s2, s18
	s_addc_u32 s3, s3, 0
	s_mov_b32 m0, s59
	v_lshl_add_u64 v[190:191], s[2:3], 0, v[170:171]
	ds_read_b128 v[146:149], v184 offset:32768
	ds_read_b128 v[150:153], v184 offset:33792
	ds_read_b128 v[154:157], v184 offset:34816
	ds_read_b128 v[158:161], v184 offset:35840
	ds_read_b128 v[162:165], v184 offset:36864
	ds_read_b128 v[166:169], v184 offset:37888
	ds_read_b128 v[178:181], v184 offset:38912
	ds_read_b128 v[186:189], v184 offset:39936
	global_load_lds_dwordx4 v[190:191], off
	v_lshl_add_u64 v[190:191], s[2:3], 0, v[172:173]
	s_mov_b32 m0, s77
	s_nop 0
	global_load_lds_dwordx4 v[190:191], off
	s_waitcnt lgkmcnt(8)
	s_add_i32 s2, 0, 0x1c000
	s_add_i32 s3, s12, s54
	v_add_u32_e32 v185, s2, v183
	ds_read_b128 v[190:193], v185
	ds_read_b128 v[194:197], v185 offset:1024
	ds_read_b128 v[198:201], v185 offset:2048
	ds_read_b128 v[226:229], v185 offset:3072
	s_nop 0
	s_waitcnt lgkmcnt(0)
	s_barrier
	s_waitcnt lgkmcnt(0)
	v_mfma_f32_16x16x32_bf16 v[126:129], v[130:133], v[146:149], v[126:129]
	v_mfma_f32_16x16x32_bf16 v[122:125], v[138:141], v[146:149], v[122:125]
	v_mfma_f32_16x16x32_bf16 v[118:121], v[130:133], v[154:157], v[118:121]
	v_mfma_f32_16x16x32_bf16 v[114:117], v[138:141], v[154:157], v[114:117]
	v_mfma_f32_16x16x32_bf16 v[110:113], v[130:133], v[162:165], v[110:113]
	v_mfma_f32_16x16x32_bf16 v[106:109], v[138:141], v[162:165], v[106:109]
	v_mfma_f32_16x16x32_bf16 v[102:105], v[130:133], v[178:181], v[102:105]
	v_mfma_f32_16x16x32_bf16 v[98:101], v[138:141], v[178:181], v[98:101]
	v_mfma_f32_16x16x32_bf16 v[126:129], v[134:137], v[150:153], v[126:129]
	v_mfma_f32_16x16x32_bf16 v[122:125], v[142:145], v[150:153], v[122:125]
	v_mfma_f32_16x16x32_bf16 v[118:121], v[134:137], v[158:161], v[118:121]
	v_mfma_f32_16x16x32_bf16 v[114:117], v[142:145], v[158:161], v[114:117]
	v_mfma_f32_16x16x32_bf16 v[110:113], v[134:137], v[166:169], v[110:113]
	v_mfma_f32_16x16x32_bf16 v[106:109], v[142:145], v[166:169], v[106:109]
	v_mfma_f32_16x16x32_bf16 v[102:105], v[134:137], v[186:189], v[102:105]
	v_mfma_f32_16x16x32_bf16 v[98:101], v[142:145], v[186:189], v[98:101]
	v_mfma_f32_16x16x32_bf16 v[62:65], v[190:193], v[146:149], v[62:65]
	v_mfma_f32_16x16x32_bf16 v[58:61], v[198:201], v[146:149], v[58:61]
	v_mfma_f32_16x16x32_bf16 v[54:57], v[190:193], v[154:157], v[54:57]
	v_mfma_f32_16x16x32_bf16 v[50:53], v[198:201], v[154:157], v[50:53]
	v_mfma_f32_16x16x32_bf16 v[46:49], v[190:193], v[162:165], v[46:49]
	v_mfma_f32_16x16x32_bf16 v[42:45], v[198:201], v[162:165], v[42:45]
	v_mfma_f32_16x16x32_bf16 v[38:41], v[190:193], v[178:181], v[38:41]
	v_mfma_f32_16x16x32_bf16 v[34:37], v[198:201], v[178:181], v[34:37]
	v_mfma_f32_16x16x32_bf16 v[62:65], v[194:197], v[150:153], v[62:65]
	v_mfma_f32_16x16x32_bf16 v[58:61], v[226:229], v[150:153], v[58:61]
	v_mfma_f32_16x16x32_bf16 v[54:57], v[194:197], v[158:161], v[54:57]
	v_mfma_f32_16x16x32_bf16 v[50:53], v[226:229], v[158:161], v[50:53]
	s_mov_b32 m0, s80
	v_lshl_add_u64 v[234:235], v[234:235], 0, s[20:21]
	v_mfma_f32_16x16x32_bf16 v[46:49], v[194:197], v[166:169], v[46:49]
	v_mfma_f32_16x16x32_bf16 v[42:45], v[226:229], v[166:169], v[42:45]
	v_mfma_f32_16x16x32_bf16 v[38:41], v[194:197], v[186:189], v[38:41]
	v_mfma_f32_16x16x32_bf16 v[34:37], v[226:229], v[186:189], v[34:37]
	s_barrier
	ds_read_b128 v[146:149], v184 offset:49152
	ds_read_b128 v[150:153], v184 offset:50176
	ds_read_b128 v[154:157], v184 offset:51200
	ds_read_b128 v[158:161], v184 offset:52224
	ds_read_b128 v[162:165], v184 offset:53248
	ds_read_b128 v[166:169], v184 offset:54272
	ds_read_b128 v[178:181], v184 offset:55296
	ds_read_b128 v[186:189], v184 offset:56320
	global_load_lds_dwordx4 v[234:235], off
	v_lshl_add_u64 v[236:237], v[236:237], 0, s[20:21]
	s_mov_b32 m0, s81
	s_nop 0
	global_load_lds_dwordx4 v[236:237], off
	v_lshl_add_u64 v[230:231], v[230:231], 0, s[20:21]
	s_mov_b32 m0, s3
	s_nop 0
	global_load_lds_dwordx4 v[230:231], off
	v_lshl_add_u64 v[230:231], v[232:233], 0, s[20:21]
	s_add_i32 m0, s3, 0x2000
	s_nop 0
	global_load_lds_dwordx4 v[230:231], off
	s_add_i32 s2, s2, s54
	v_lshl_add_u64 v[242:243], v[242:243], 0, s[20:21]
	s_mov_b32 m0, s2
	s_nop 0
	global_load_lds_dwordx4 v[242:243], off
	v_lshl_add_u64 v[244:245], v[244:245], 0, s[20:21]
	s_add_i32 m0, s2, 0x2000
	s_nop 0
	global_load_lds_dwordx4 v[244:245], off
	s_waitcnt vmcnt(6)
	s_nop 0
	s_waitcnt lgkmcnt(0)
	s_barrier
	s_waitcnt lgkmcnt(0)
	v_mfma_f32_16x16x32_bf16 v[94:97], v[130:133], v[146:149], v[94:97]
	v_mfma_f32_16x16x32_bf16 v[90:93], v[138:141], v[146:149], v[90:93]
	v_mfma_f32_16x16x32_bf16 v[86:89], v[130:133], v[154:157], v[86:89]
	v_mfma_f32_16x16x32_bf16 v[82:85], v[138:141], v[154:157], v[82:85]
	v_mfma_f32_16x16x32_bf16 v[78:81], v[130:133], v[162:165], v[78:81]
	v_mfma_f32_16x16x32_bf16 v[74:77], v[138:141], v[162:165], v[74:77]
	v_mfma_f32_16x16x32_bf16 v[70:73], v[130:133], v[178:181], v[70:73]
	v_mfma_f32_16x16x32_bf16 v[66:69], v[138:141], v[178:181], v[66:69]
	v_mfma_f32_16x16x32_bf16 v[94:97], v[134:137], v[150:153], v[94:97]
	v_mfma_f32_16x16x32_bf16 v[90:93], v[142:145], v[150:153], v[90:93]
	v_mfma_f32_16x16x32_bf16 v[86:89], v[134:137], v[158:161], v[86:89]
	v_mfma_f32_16x16x32_bf16 v[82:85], v[142:145], v[158:161], v[82:85]
	v_mfma_f32_16x16x32_bf16 v[78:81], v[134:137], v[166:169], v[78:81]
	v_mfma_f32_16x16x32_bf16 v[74:77], v[142:145], v[166:169], v[74:77]
	v_mfma_f32_16x16x32_bf16 v[70:73], v[134:137], v[186:189], v[70:73]
	v_mfma_f32_16x16x32_bf16 v[66:69], v[142:145], v[186:189], v[66:69]
	v_mfma_f32_16x16x32_bf16 v[30:33], v[190:193], v[146:149], v[30:33]
	v_mfma_f32_16x16x32_bf16 v[26:29], v[198:201], v[146:149], v[26:29]
	v_mfma_f32_16x16x32_bf16 v[22:25], v[190:193], v[154:157], v[22:25]
	v_mfma_f32_16x16x32_bf16 v[18:21], v[198:201], v[154:157], v[18:21]
	v_mfma_f32_16x16x32_bf16 v[14:17], v[190:193], v[162:165], v[14:17]
	v_mfma_f32_16x16x32_bf16 v[10:13], v[198:201], v[162:165], v[10:13]
	v_mfma_f32_16x16x32_bf16 v[6:9], v[190:193], v[178:181], v[6:9]
	v_mfma_f32_16x16x32_bf16 v[2:5], v[198:201], v[178:181], v[2:5]
	v_mfma_f32_16x16x32_bf16 v[30:33], v[194:197], v[150:153], v[30:33]
	v_mfma_f32_16x16x32_bf16 v[26:29], v[226:229], v[150:153], v[26:29]
	v_mfma_f32_16x16x32_bf16 v[22:25], v[194:197], v[158:161], v[22:25]
	v_mfma_f32_16x16x32_bf16 v[18:21], v[226:229], v[158:161], v[18:21]
	s_add_u32 s34, s34, 0x100
	s_addc_u32 s35, s35, 0
	s_add_u32 s89, s89, 0x100
	s_addc_u32 s90, s90, 0
	s_cmp_ge_i32 s91, s44
	s_mov_b32 s2, s91
	v_mfma_f32_16x16x32_bf16 v[14:17], v[194:197], v[166:169], v[14:17]
	v_mfma_f32_16x16x32_bf16 v[10:13], v[226:229], v[166:169], v[10:13]
	v_mfma_f32_16x16x32_bf16 v[6:9], v[194:197], v[186:189], v[6:9]
	v_mfma_f32_16x16x32_bf16 v[2:5], v[226:229], v[186:189], v[2:5]
	s_barrier
	s_cbranch_scc1 .Lpeel_x_1
.LBB0_182:
	s_add_i32 s91, s2, 2
	s_add_u32 s12, s34, 0x80
	s_addc_u32 s3, s35, 0
	s_add_i32 s13, 0, 0x10000
	v_add_u32_e32 v142, s13, v183
	ds_read_b128 v[130:133], v142
	ds_read_b128 v[134:137], v142 offset:1024
	ds_read_b128 v[138:141], v142 offset:2048
	ds_read_b128 v[142:145], v142 offset:3072
	s_cmp_eq_u32 s88, s2
	s_cselect_b32 s2, s0, s12
	s_cselect_b32 s3, s1, s3
	s_cselect_b32 s43, s41, s90
	s_cselect_b32 s42, s40, s89
	v_lshl_add_u64 v[190:191], s[34:35], 0, v[174:175]
	s_add_i32 m0, s55, 0xc000
	ds_read_b128 v[146:149], v184
	ds_read_b128 v[150:153], v184 offset:1024
	ds_read_b128 v[154:157], v184 offset:2048
	ds_read_b128 v[158:161], v184 offset:3072
	ds_read_b128 v[162:165], v184 offset:4096
	ds_read_b128 v[166:169], v184 offset:5120
	ds_read_b128 v[178:181], v184 offset:6144
	ds_read_b128 v[186:189], v184 offset:7168
	global_load_lds_dwordx4 v[190:191], off
	v_lshl_add_u64 v[190:191], s[34:35], 0, v[176:177]
	s_add_i32 m0, s55, 0xe000
	s_nop 0
	global_load_lds_dwordx4 v[190:191], off
	s_waitcnt lgkmcnt(8)
	s_add_i32 s92, 0, 0x14000
	s_add_i32 s12, s13, s54
	v_add_u32_e32 v185, s92, v183
	ds_read_b128 v[190:193], v185
	ds_read_b128 v[194:197], v185 offset:1024
	ds_read_b128 v[198:201], v185 offset:2048
	ds_read_b128 v[226:229], v185 offset:3072
	s_nop 0
	s_waitcnt lgkmcnt(0)
	s_barrier
	s_waitcnt lgkmcnt(0)
	v_mfma_f32_16x16x32_bf16 v[126:129], v[130:133], v[146:149], v[126:129]
	v_mfma_f32_16x16x32_bf16 v[122:125], v[138:141], v[146:149], v[122:125]
	v_mfma_f32_16x16x32_bf16 v[118:121], v[130:133], v[154:157], v[118:121]
	v_mfma_f32_16x16x32_bf16 v[114:117], v[138:141], v[154:157], v[114:117]
	v_mfma_f32_16x16x32_bf16 v[110:113], v[130:133], v[162:165], v[110:113]
	v_mfma_f32_16x16x32_bf16 v[106:109], v[138:141], v[162:165], v[106:109]
	v_mfma_f32_16x16x32_bf16 v[102:105], v[130:133], v[178:181], v[102:105]
	v_mfma_f32_16x16x32_bf16 v[98:101], v[138:141], v[178:181], v[98:101]
	v_mfma_f32_16x16x32_bf16 v[126:129], v[134:137], v[150:153], v[126:129]
	v_mfma_f32_16x16x32_bf16 v[122:125], v[142:145], v[150:153], v[122:125]
	v_mfma_f32_16x16x32_bf16 v[118:121], v[134:137], v[158:161], v[118:121]
	v_mfma_f32_16x16x32_bf16 v[114:117], v[142:145], v[158:161], v[114:117]
	v_mfma_f32_16x16x32_bf16 v[110:113], v[134:137], v[166:169], v[110:113]
	v_mfma_f32_16x16x32_bf16 v[106:109], v[142:145], v[166:169], v[106:109]
	v_mfma_f32_16x16x32_bf16 v[102:105], v[134:137], v[186:189], v[102:105]
	v_mfma_f32_16x16x32_bf16 v[98:101], v[142:145], v[186:189], v[98:101]
	v_mfma_f32_16x16x32_bf16 v[62:65], v[190:193], v[146:149], v[62:65]
	v_mfma_f32_16x16x32_bf16 v[58:61], v[198:201], v[146:149], v[58:61]
	v_mfma_f32_16x16x32_bf16 v[54:57], v[190:193], v[154:157], v[54:57]
	v_mfma_f32_16x16x32_bf16 v[50:53], v[198:201], v[154:157], v[50:53]
	v_mfma_f32_16x16x32_bf16 v[46:49], v[190:193], v[162:165], v[46:49]
	v_mfma_f32_16x16x32_bf16 v[42:45], v[198:201], v[162:165], v[42:45]
	v_mfma_f32_16x16x32_bf16 v[38:41], v[190:193], v[178:181], v[38:41]
	v_mfma_f32_16x16x32_bf16 v[34:37], v[198:201], v[178:181], v[34:37]
	v_mfma_f32_16x16x32_bf16 v[62:65], v[194:197], v[150:153], v[62:65]
	v_mfma_f32_16x16x32_bf16 v[58:61], v[226:229], v[150:153], v[58:61]
	v_mfma_f32_16x16x32_bf16 v[54:57], v[194:197], v[158:161], v[54:57]
	v_mfma_f32_16x16x32_bf16 v[50:53], v[226:229], v[158:161], v[50:53]
	s_mov_b32 m0, s55
	v_lshl_add_u64 v[234:235], s[2:3], 0, v[170:171]
	v_mfma_f32_16x16x32_bf16 v[46:49], v[194:197], v[166:169], v[46:49]
	v_mfma_f32_16x16x32_bf16 v[42:45], v[226:229], v[166:169], v[42:45]
	v_mfma_f32_16x16x32_bf16 v[38:41], v[194:197], v[186:189], v[38:41]
	v_mfma_f32_16x16x32_bf16 v[34:37], v[226:229], v[186:189], v[34:37]
	s_barrier
	ds_read_b128 v[146:149], v184 offset:16384
	ds_read_b128 v[150:153], v184 offset:17408
	ds_read_b128 v[154:157], v184 offset:18432
	ds_read_b128 v[158:161], v184 offset:19456
	ds_read_b128 v[162:165], v184 offset:20480
	ds_read_b128 v[166:169], v184 offset:21504
	ds_read_b128 v[178:181], v184 offset:22528
	ds_read_b128 v[186:189], v184 offset:23552
	global_load_lds_dwordx4 v[234:235], off
	v_lshl_add_u64 v[236:237], s[2:3], 0, v[172:173]
	s_mov_b32 m0, s58
	s_nop 0
	global_load_lds_dwordx4 v[236:237], off
	v_lshl_add_u64 v[230:231], s[42:43], 0, v[170:171]
	s_mov_b32 m0, s12
	s_nop 0
	global_load_lds_dwordx4 v[230:231], off
	v_lshl_add_u64 v[232:233], s[42:43], 0, v[172:173]
	s_add_i32 m0, s12, 0x2000
	s_nop 0
	global_load_lds_dwordx4 v[232:233], off
	s_add_u32 s12, s42, s18
	s_addc_u32 s13, s43, 0
	s_add_i32 s42, s92, s54
	v_lshl_add_u64 v[242:243], s[12:13], 0, v[170:171]
	s_mov_b32 m0, s42
	v_lshl_add_u64 v[244:245], s[12:13], 0, v[172:173]
	global_load_lds_dwordx4 v[242:243], off
	s_add_i32 m0, s42, 0x2000
	s_nop 0
	global_load_lds_dwordx4 v[244:245], off
	s_waitcnt vmcnt(6)
	s_nop 0
	s_waitcnt lgkmcnt(0)
	s_barrier
	s_waitcnt lgkmcnt(0)
	s_nop 0
	v_mfma_f32_16x16x32_bf16 v[94:97], v[130:133], v[146:149], v[94:97]
	v_mfma_f32_16x16x32_bf16 v[90:93], v[138:141], v[146:149], v[90:93]
	v_mfma_f32_16x16x32_bf16 v[86:89], v[130:133], v[154:157], v[86:89]
	v_mfma_f32_16x16x32_bf16 v[82:85], v[138:141], v[154:157], v[82:85]
	v_mfma_f32_16x16x32_bf16 v[78:81], v[130:133], v[162:165], v[78:81]
	v_mfma_f32_16x16x32_bf16 v[74:77], v[138:141], v[162:165], v[74:77]
	v_mfma_f32_16x16x32_bf16 v[70:73], v[130:133], v[178:181], v[70:73]
	v_mfma_f32_16x16x32_bf16 v[66:69], v[138:141], v[178:181], v[66:69]
	v_mfma_f32_16x16x32_bf16 v[94:97], v[134:137], v[150:153], v[94:97]
	v_mfma_f32_16x16x32_bf16 v[90:93], v[142:145], v[150:153], v[90:93]
	v_mfma_f32_16x16x32_bf16 v[86:89], v[134:137], v[158:161], v[86:89]
	v_mfma_f32_16x16x32_bf16 v[82:85], v[142:145], v[158:161], v[82:85]
	v_mfma_f32_16x16x32_bf16 v[78:81], v[134:137], v[166:169], v[78:81]
	v_mfma_f32_16x16x32_bf16 v[74:77], v[142:145], v[166:169], v[74:77]
	v_mfma_f32_16x16x32_bf16 v[70:73], v[134:137], v[186:189], v[70:73]
	v_mfma_f32_16x16x32_bf16 v[66:69], v[142:145], v[186:189], v[66:69]
	v_mfma_f32_16x16x32_bf16 v[30:33], v[190:193], v[146:149], v[30:33]
	v_mfma_f32_16x16x32_bf16 v[26:29], v[198:201], v[146:149], v[26:29]
	v_mfma_f32_16x16x32_bf16 v[22:25], v[190:193], v[154:157], v[22:25]
	v_mfma_f32_16x16x32_bf16 v[18:21], v[198:201], v[154:157], v[18:21]
	v_mfma_f32_16x16x32_bf16 v[14:17], v[190:193], v[162:165], v[14:17]
	v_mfma_f32_16x16x32_bf16 v[10:13], v[198:201], v[162:165], v[10:13]
	v_mfma_f32_16x16x32_bf16 v[6:9], v[190:193], v[178:181], v[6:9]
	v_mfma_f32_16x16x32_bf16 v[2:5], v[198:201], v[178:181], v[2:5]
	v_mfma_f32_16x16x32_bf16 v[30:33], v[194:197], v[150:153], v[30:33]
	v_mfma_f32_16x16x32_bf16 v[26:29], v[226:229], v[150:153], v[26:29]
	v_mfma_f32_16x16x32_bf16 v[22:25], v[194:197], v[158:161], v[22:25]
	v_mfma_f32_16x16x32_bf16 v[18:21], v[226:229], v[158:161], v[18:21]
	s_add_i32 s12, 0, 0x18000
	v_add_u32_e32 v142, s12, v183
	v_mfma_f32_16x16x32_bf16 v[14:17], v[194:197], v[166:169], v[14:17]
	v_mfma_f32_16x16x32_bf16 v[10:13], v[226:229], v[166:169], v[10:13]
	v_mfma_f32_16x16x32_bf16 v[6:9], v[194:197], v[186:189], v[6:9]
	v_mfma_f32_16x16x32_bf16 v[2:5], v[226:229], v[186:189], v[2:5]
	s_barrier
	ds_read_b128 v[130:133], v142
	ds_read_b128 v[134:137], v142 offset:1024
	ds_read_b128 v[138:141], v142 offset:2048
	ds_read_b128 v[142:145], v142 offset:3072
	s_add_u32 s2, s2, s18
	s_addc_u32 s3, s3, 0
	s_mov_b32 m0, s59
	v_lshl_add_u64 v[190:191], s[2:3], 0, v[170:171]
	ds_read_b128 v[146:149], v184 offset:32768
	ds_read_b128 v[150:153], v184 offset:33792
	ds_read_b128 v[154:157], v184 offset:34816
	ds_read_b128 v[158:161], v184 offset:35840
	ds_read_b128 v[162:165], v184 offset:36864
	ds_read_b128 v[166:169], v184 offset:37888
	ds_read_b128 v[178:181], v184 offset:38912
	ds_read_b128 v[186:189], v184 offset:39936
	global_load_lds_dwordx4 v[190:191], off
	v_lshl_add_u64 v[190:191], s[2:3], 0, v[172:173]
	s_mov_b32 m0, s77
	s_nop 0
	global_load_lds_dwordx4 v[190:191], off
	s_waitcnt lgkmcnt(8)
	s_add_i32 s2, 0, 0x1c000
	s_add_i32 s3, s12, s54
	v_add_u32_e32 v185, s2, v183
	ds_read_b128 v[190:193], v185
	ds_read_b128 v[194:197], v185 offset:1024
	ds_read_b128 v[198:201], v185 offset:2048
	ds_read_b128 v[226:229], v185 offset:3072
	s_nop 0
	s_waitcnt lgkmcnt(0)
	s_barrier
	s_waitcnt lgkmcnt(0)
	v_mfma_f32_16x16x32_bf16 v[126:129], v[130:133], v[146:149], v[126:129]
	v_mfma_f32_16x16x32_bf16 v[122:125], v[138:141], v[146:149], v[122:125]
	v_mfma_f32_16x16x32_bf16 v[118:121], v[130:133], v[154:157], v[118:121]
	v_mfma_f32_16x16x32_bf16 v[114:117], v[138:141], v[154:157], v[114:117]
	v_mfma_f32_16x16x32_bf16 v[110:113], v[130:133], v[162:165], v[110:113]
	v_mfma_f32_16x16x32_bf16 v[106:109], v[138:141], v[162:165], v[106:109]
	v_mfma_f32_16x16x32_bf16 v[102:105], v[130:133], v[178:181], v[102:105]
	v_mfma_f32_16x16x32_bf16 v[98:101], v[138:141], v[178:181], v[98:101]
	v_mfma_f32_16x16x32_bf16 v[126:129], v[134:137], v[150:153], v[126:129]
	v_mfma_f32_16x16x32_bf16 v[122:125], v[142:145], v[150:153], v[122:125]
	v_mfma_f32_16x16x32_bf16 v[118:121], v[134:137], v[158:161], v[118:121]
	v_mfma_f32_16x16x32_bf16 v[114:117], v[142:145], v[158:161], v[114:117]
	v_mfma_f32_16x16x32_bf16 v[110:113], v[134:137], v[166:169], v[110:113]
	v_mfma_f32_16x16x32_bf16 v[106:109], v[142:145], v[166:169], v[106:109]
	v_mfma_f32_16x16x32_bf16 v[102:105], v[134:137], v[186:189], v[102:105]
	v_mfma_f32_16x16x32_bf16 v[98:101], v[142:145], v[186:189], v[98:101]
	v_mfma_f32_16x16x32_bf16 v[62:65], v[190:193], v[146:149], v[62:65]
	v_mfma_f32_16x16x32_bf16 v[58:61], v[198:201], v[146:149], v[58:61]
	v_mfma_f32_16x16x32_bf16 v[54:57], v[190:193], v[154:157], v[54:57]
	v_mfma_f32_16x16x32_bf16 v[50:53], v[198:201], v[154:157], v[50:53]
	v_mfma_f32_16x16x32_bf16 v[46:49], v[190:193], v[162:165], v[46:49]
	v_mfma_f32_16x16x32_bf16 v[42:45], v[198:201], v[162:165], v[42:45]
	v_mfma_f32_16x16x32_bf16 v[38:41], v[190:193], v[178:181], v[38:41]
	v_mfma_f32_16x16x32_bf16 v[34:37], v[198:201], v[178:181], v[34:37]
	v_mfma_f32_16x16x32_bf16 v[62:65], v[194:197], v[150:153], v[62:65]
	v_mfma_f32_16x16x32_bf16 v[58:61], v[226:229], v[150:153], v[58:61]
	v_mfma_f32_16x16x32_bf16 v[54:57], v[194:197], v[158:161], v[54:57]
	v_mfma_f32_16x16x32_bf16 v[50:53], v[226:229], v[158:161], v[50:53]
	s_mov_b32 m0, s80
	v_lshl_add_u64 v[234:235], v[234:235], 0, s[20:21]
	v_mfma_f32_16x16x32_bf16 v[46:49], v[194:197], v[166:169], v[46:49]
	v_mfma_f32_16x16x32_bf16 v[42:45], v[226:229], v[166:169], v[42:45]
	v_mfma_f32_16x16x32_bf16 v[38:41], v[194:197], v[186:189], v[38:41]
	v_mfma_f32_16x16x32_bf16 v[34:37], v[226:229], v[186:189], v[34:37]
	s_barrier
	ds_read_b128 v[146:149], v184 offset:49152
	ds_read_b128 v[150:153], v184 offset:50176
	ds_read_b128 v[154:157], v184 offset:51200
	ds_read_b128 v[158:161], v184 offset:52224
	ds_read_b128 v[162:165], v184 offset:53248
	ds_read_b128 v[166:169], v184 offset:54272
	ds_read_b128 v[178:181], v184 offset:55296
	ds_read_b128 v[186:189], v184 offset:56320
	global_load_lds_dwordx4 v[234:235], off
	v_lshl_add_u64 v[236:237], v[236:237], 0, s[20:21]
	s_mov_b32 m0, s81
	s_nop 0
	global_load_lds_dwordx4 v[236:237], off
	v_lshl_add_u64 v[230:231], v[230:231], 0, s[20:21]
	s_mov_b32 m0, s3
	s_nop 0
	global_load_lds_dwordx4 v[230:231], off
	v_lshl_add_u64 v[230:231], v[232:233], 0, s[20:21]
	s_add_i32 m0, s3, 0x2000
	s_nop 0
	global_load_lds_dwordx4 v[230:231], off
	s_add_i32 s2, s2, s54
	v_lshl_add_u64 v[242:243], v[242:243], 0, s[20:21]
	s_mov_b32 m0, s2
	s_nop 0
	global_load_lds_dwordx4 v[242:243], off
	v_lshl_add_u64 v[244:245], v[244:245], 0, s[20:21]
	s_add_i32 m0, s2, 0x2000
	s_nop 0
	global_load_lds_dwordx4 v[244:245], off
	s_waitcnt vmcnt(6)
	s_nop 0
	s_waitcnt lgkmcnt(0)
	s_barrier
	s_waitcnt lgkmcnt(0)
	v_mfma_f32_16x16x32_bf16 v[94:97], v[130:133], v[146:149], v[94:97]
	v_mfma_f32_16x16x32_bf16 v[90:93], v[138:141], v[146:149], v[90:93]
	v_mfma_f32_16x16x32_bf16 v[86:89], v[130:133], v[154:157], v[86:89]
	v_mfma_f32_16x16x32_bf16 v[82:85], v[138:141], v[154:157], v[82:85]
	v_mfma_f32_16x16x32_bf16 v[78:81], v[130:133], v[162:165], v[78:81]
	v_mfma_f32_16x16x32_bf16 v[74:77], v[138:141], v[162:165], v[74:77]
	v_mfma_f32_16x16x32_bf16 v[70:73], v[130:133], v[178:181], v[70:73]
	v_mfma_f32_16x16x32_bf16 v[66:69], v[138:141], v[178:181], v[66:69]
	v_mfma_f32_16x16x32_bf16 v[94:97], v[134:137], v[150:153], v[94:97]
	v_mfma_f32_16x16x32_bf16 v[90:93], v[142:145], v[150:153], v[90:93]
	v_mfma_f32_16x16x32_bf16 v[86:89], v[134:137], v[158:161], v[86:89]
	v_mfma_f32_16x16x32_bf16 v[82:85], v[142:145], v[158:161], v[82:85]
	v_mfma_f32_16x16x32_bf16 v[78:81], v[134:137], v[166:169], v[78:81]
	v_mfma_f32_16x16x32_bf16 v[74:77], v[142:145], v[166:169], v[74:77]
	v_mfma_f32_16x16x32_bf16 v[70:73], v[134:137], v[186:189], v[70:73]
	v_mfma_f32_16x16x32_bf16 v[66:69], v[142:145], v[186:189], v[66:69]
	v_mfma_f32_16x16x32_bf16 v[30:33], v[190:193], v[146:149], v[30:33]
	v_mfma_f32_16x16x32_bf16 v[26:29], v[198:201], v[146:149], v[26:29]
	v_mfma_f32_16x16x32_bf16 v[22:25], v[190:193], v[154:157], v[22:25]
	v_mfma_f32_16x16x32_bf16 v[18:21], v[198:201], v[154:157], v[18:21]
	v_mfma_f32_16x16x32_bf16 v[14:17], v[190:193], v[162:165], v[14:17]
	v_mfma_f32_16x16x32_bf16 v[10:13], v[198:201], v[162:165], v[10:13]
	v_mfma_f32_16x16x32_bf16 v[6:9], v[190:193], v[178:181], v[6:9]
	v_mfma_f32_16x16x32_bf16 v[2:5], v[198:201], v[178:181], v[2:5]
	v_mfma_f32_16x16x32_bf16 v[30:33], v[194:197], v[150:153], v[30:33]
	v_mfma_f32_16x16x32_bf16 v[26:29], v[226:229], v[150:153], v[26:29]
	v_mfma_f32_16x16x32_bf16 v[22:25], v[194:197], v[158:161], v[22:25]
	v_mfma_f32_16x16x32_bf16 v[18:21], v[226:229], v[158:161], v[18:21]
	s_add_u32 s34, s34, 0x100
	s_addc_u32 s35, s35, 0
	s_add_u32 s89, s89, 0x100
	s_addc_u32 s90, s90, 0
	s_cmp_ge_i32 s91, s44
	s_mov_b32 s2, s91
	v_mfma_f32_16x16x32_bf16 v[14:17], v[194:197], v[166:169], v[14:17]
	v_mfma_f32_16x16x32_bf16 v[10:13], v[226:229], v[166:169], v[10:13]
	v_mfma_f32_16x16x32_bf16 v[6:9], v[194:197], v[186:189], v[6:9]
	v_mfma_f32_16x16x32_bf16 v[2:5], v[226:229], v[186:189], v[2:5]
	s_barrier
	s_cbranch_scc0 .LBB0_182
